# attention loop-edge: issue K ds_reads right after barrier, before global-load block (on v22)
# baseline (speedup 1.0000x reference)
; #define FL_GLOADK(j) do { \
;     _Pragma("unroll") for (int i_ = 0; i_ < KPT; ++i_) { const int ci = tid + 512 * i_; if (ci < NKC) { const int key = ci / KCH, ch = ci - key * KCH; \
;         kreg[i_] = *(const u32x4*)(K0 + (size_t)(64 * (j) + key) * kpitch + ch * 8); } } } while (0)
; #define FL_LSTOREK(buf) do { \
;     _Pragma("unroll") for (int i_ = 0; i_ < KPT; ++i_) { const int ci = tid + 512 * i_; if (ci < NKC) { const int key = ci / KCH, ch = ci - key * KCH; \
;         *(LAS u32x4*)(lds + (buf) * KB + (key * KP + ch * 8) * 2) = kreg[i_]; } } } while (0)
; #define FL_GLOADV(j) do { \
;     _Pragma("unroll") for (int i_ = 0; i_ < VPT; ++i_) { const int ci = tid + 512 * i_; const int d = ci >> 3, ch = ci & 7; kreg[i_] = *(const u32x4*)(VT + (size_t)d * vpitch + 64 * (j) + ch * 8); } } while (0)
; #define FL_LSTOREV(buf) do { \
;     _Pragma("unroll") for (int i_ = 0; i_ < VPT; ++i_) { const int ci = tid + 512 * i_; const int d = ci >> 3, ch = ci & 7; LAS u32x2* p_ = (LAS u32x2*)(lds + 2 * KB + (buf) * VB + (d * VP + ch * 8) * 2); \
;         p_[0] = (u32x2){kreg[i_].x, kreg[i_].y}; p_[1] = (u32x2){kreg[i_].z, kreg[i_].w}; } } while (0)
; template <int DQK, int DV, int MODE>
; __device__ __forceinline__ void flash_unit(LAS unsigned char* lds, const bf16* Qp, int qpitch, const bf16* K0, int kpitch, const bf16* K1, const bf16* VT, int vpitch,
;                                            bf16* Op, int opitch, int NT, int jbase, int qpos0) {
;     ...
;     for (int j = 0; j < NT; ++j) {
;         const int buf = j & 1;
;         if (j + 1 < NT) { if constexpr (MODE == 1) { FL_GLOADK(j + 1); FL_LSTOREK(buf ^ 1); FL_GLOADV(j + 1); FL_LSTOREV(buf ^ 1); } else { FL_GLOAD(j + 1); } }
;         if (MODE == 1 || j <= jmax) { FL_X(j); FL_Y(j); }
.LBB0_550:
	s_add_i32 s7, s64, 3
	s_and_b32 s6, s7, 1
	s_cmp_gt_i32 s7, s26
	s_cbranch_scc1 .Lat_nokr
	s_mul_i32 s7, s6, 0x3400
	v_add_u32_e32 v0, s7, v169
	ds_read_b128 v[6:9], v0
	ds_read_b128 v[10:13], v0 offset:32
	ds_read_b128 v[128:131], v0 offset:6656
	ds_read_b128 v[132:135], v0 offset:6688
	ds_read_b128 v[136:139], v0 offset:64
	ds_read_b128 v[140:143], v0 offset:96
	ds_read_b128 v[144:147], v0 offset:6720
	ds_read_b128 v[148:151], v0 offset:6752
	ds_read_b128 v[180:183], v0 offset:128
	ds_read_b128 v[184:187], v0 offset:160
	ds_read_b128 v[188:191], v0 offset:6784
	ds_read_b128 v[192:195], v0 offset:6816
.Lat_nokr:
	s_and_saveexec_b64 s[98:99], s[2:3]
	s_cbranch_execz .LBB0_552
	v_lshlrev_b64 v[2:3], v168, v[170:171]
	v_lshl_add_u64 v[2:3], v[166:167], 0, v[2:3]
	global_load_dwordx4 v[96:99], v[2:3], off
.LBB0_552:
	s_or_b64 exec, exec, s[98:99]
	s_and_saveexec_b64 s[98:99], s[4:5]
	s_cbranch_execz .LBB0_554
	v_lshlrev_b64 v[2:3], v164, v[172:173]
	v_lshl_add_u64 v[2:3], v[162:163], 0, v[2:3]
	global_load_dwordx4 v[100:103], v[2:3], off
.LBB0_554:
	s_or_b64 exec, exec, s[98:99]
	global_load_dwordx4 v[2:5], v[174:175], off
	s_add_i32 s7, s64, 3
	s_cmp_gt_i32 s7, s26
	s_cbranch_scc1 .LBB0_558
	s_waitcnt lgkmcnt(8)
	v_mfma_f32_32x32x16_bf16 v[80:95], v[6:9], v[116:119], v[48:63]
	v_mfma_f32_32x32x16_bf16 v[64:79], v[128:131], v[116:119], v[48:63]
	v_mfma_f32_32x32x16_bf16 v[80:95], v[10:13], v[112:115], v[80:95]
	v_mfma_f32_32x32x16_bf16 v[64:79], v[132:135], v[112:115], v[64:79]
	s_waitcnt lgkmcnt(4)
	v_mfma_f32_32x32x16_bf16 v[80:95], v[136:139], v[108:111], v[80:95]
	v_mfma_f32_32x32x16_bf16 v[64:79], v[144:147], v[108:111], v[64:79]
	v_mfma_f32_32x32x16_bf16 v[80:95], v[140:143], v[104:107], v[80:95]
	v_mfma_f32_32x32x16_bf16 v[64:79], v[148:151], v[104:107], v[64:79]
	s_waitcnt lgkmcnt(0)
	v_mfma_f32_32x32x16_bf16 v[80:95], v[180:183], v[120:123], v[80:95]
	v_mfma_f32_32x32x16_bf16 v[64:79], v[188:191], v[120:123], v[64:79]
	v_mfma_f32_32x32x16_bf16 v[80:95], v[184:187], v[124:127], v[80:95]
	v_mfma_f32_32x32x16_bf16 v[64:79], v[192:195], v[124:127], v[64:79]
	s_mul_i32 s7, s6, 0x2200
	v_add_u32_e32 v0, s7, v165
	v_add_u32_e32 v6, 0x6800, v0
	v_add_u32_e32 v0, 0x7800, v0
	ds_read2_b64 v[148:151], v6 offset1:2
	ds_read2_b64 v[144:147], v6 offset0:4 offset1:6
	ds_read2_b64 v[140:143], v6 offset0:8 offset1:10
	ds_read2_b64 v[136:139], v6 offset0:12 offset1:14
	ds_read2_b64 v[132:135], v0 offset0:32 offset1:34
	ds_read2_b64 v[128:131], v0 offset0:36 offset1:38
	ds_read2_b64 v[10:13], v0 offset0:40 offset1:42
	ds_read2_b64 v[6:9], v0 offset0:44 offset1:46
	v_max_f32_e32 v15, v65, v65
	v_max_f32_e32 v161, v64, v64
	v_max_f32_e32 v15, v161, v15
	v_max3_f32 v0, v80, v81, v82
	v_max3_f32 v15, v15, v66, v67
	v_max3_f32 v0, v0, v83, v84
	v_max3_f32 v15, v15, v68, v69
	v_max3_f32 v0, v0, v85, v86
	v_max3_f32 v15, v15, v70, v71
	v_max3_f32 v0, v0, v87, v88
	v_max3_f32 v15, v15, v72, v73
	v_max3_f32 v0, v0, v89, v90
	v_max3_f32 v15, v15, v74, v75
	v_max3_f32 v0, v0, v91, v92
	v_max3_f32 v15, v15, v76, v77
	v_max3_f32 v0, v0, v93, v94
	v_max3_f32 v15, v15, v78, v79
	v_max3_f32 v0, v0, v95, v15
	v_mov_b32_e32 v15, v0
	s_nop 1
	v_permlane32_swap_b32_e32 v0, v15
	v_max_f32_e32 v15, v15, v15
	v_max_f32_e32 v0, v0, v0
	v_max_f32_e32 v0, v0, v15
	v_cmp_lt_f32_e32 vcc, s56, v0
	s_cbranch_vccz .LBB0_557
	s_nop 0
	v_cndmask_b32_e32 v0, 0, v0, vcc
	v_exp_f32_e64 v180, -v0
	v_add_f32_e32 v158, v158, v0
	v_xor_b32_e32 v48, 0x80000000, v158
	v_mov_b32_e32 v49, v48
	v_mov_b32_e32 v50, v48
	v_mov_b32_e32 v51, v48
	v_mov_b32_e32 v52, v48
	v_mov_b32_e32 v53, v48
	v_mov_b32_e32 v54, v48
	v_mov_b32_e32 v55, v48
	v_mov_b32_e32 v56, v48
	v_mov_b32_e32 v57, v48
	v_mov_b32_e32 v58, v48
	v_mov_b32_e32 v59, v48
	v_mov_b32_e32 v60, v48
	v_mov_b32_e32 v61, v48
	v_mov_b32_e32 v62, v48
	v_mov_b32_e32 v63, v48
	v_pk_add_f32 v[80:81], v[80:81], v[0:1] op_sel_hi:[1,0] neg_lo:[0,1] neg_hi:[0,1]
	v_pk_add_f32 v[64:65], v[64:65], v[0:1] op_sel_hi:[1,0] neg_lo:[0,1] neg_hi:[0,1]
	v_pk_add_f32 v[82:83], v[82:83], v[0:1] op_sel_hi:[1,0] neg_lo:[0,1] neg_hi:[0,1]
	v_pk_add_f32 v[66:67], v[66:67], v[0:1] op_sel_hi:[1,0] neg_lo:[0,1] neg_hi:[0,1]
	v_pk_add_f32 v[84:85], v[84:85], v[0:1] op_sel_hi:[1,0] neg_lo:[0,1] neg_hi:[0,1]
	v_pk_add_f32 v[68:69], v[68:69], v[0:1] op_sel_hi:[1,0] neg_lo:[0,1] neg_hi:[0,1]
	v_pk_add_f32 v[86:87], v[86:87], v[0:1] op_sel_hi:[1,0] neg_lo:[0,1] neg_hi:[0,1]
	v_pk_add_f32 v[70:71], v[70:71], v[0:1] op_sel_hi:[1,0] neg_lo:[0,1] neg_hi:[0,1]
	v_pk_add_f32 v[88:89], v[88:89], v[0:1] op_sel_hi:[1,0] neg_lo:[0,1] neg_hi:[0,1]
	v_pk_add_f32 v[72:73], v[72:73], v[0:1] op_sel_hi:[1,0] neg_lo:[0,1] neg_hi:[0,1]
	v_pk_add_f32 v[90:91], v[90:91], v[0:1] op_sel_hi:[1,0] neg_lo:[0,1] neg_hi:[0,1]
	v_pk_add_f32 v[74:75], v[74:75], v[0:1] op_sel_hi:[1,0] neg_lo:[0,1] neg_hi:[0,1]
	v_pk_add_f32 v[92:93], v[92:93], v[0:1] op_sel_hi:[1,0] neg_lo:[0,1] neg_hi:[0,1]
	v_pk_add_f32 v[76:77], v[76:77], v[0:1] op_sel_hi:[1,0] neg_lo:[0,1] neg_hi:[0,1]
	v_pk_add_f32 v[94:95], v[94:95], v[0:1] op_sel_hi:[1,0] neg_lo:[0,1] neg_hi:[0,1]
	v_pk_add_f32 v[78:79], v[78:79], v[0:1] op_sel_hi:[1,0] neg_lo:[0,1] neg_hi:[0,1]
	v_pk_mul_f32 v[46:47], v[46:47], v[180:181] op_sel_hi:[1,0]
	v_pk_mul_f32 v[44:45], v[44:45], v[180:181] op_sel_hi:[1,0]
	v_pk_mul_f32 v[42:43], v[42:43], v[180:181] op_sel_hi:[1,0]
	v_pk_mul_f32 v[40:41], v[40:41], v[180:181] op_sel_hi:[1,0]
	v_pk_mul_f32 v[38:39], v[38:39], v[180:181] op_sel_hi:[1,0]
	v_pk_mul_f32 v[36:37], v[36:37], v[180:181] op_sel_hi:[1,0]
	v_pk_mul_f32 v[34:35], v[34:35], v[180:181] op_sel_hi:[1,0]
	v_pk_mul_f32 v[32:33], v[32:33], v[180:181] op_sel_hi:[1,0]
	v_pk_mul_f32 v[30:31], v[30:31], v[180:181] op_sel_hi:[1,0]
	v_pk_mul_f32 v[28:29], v[28:29], v[180:181] op_sel_hi:[1,0]
	v_pk_mul_f32 v[26:27], v[26:27], v[180:181] op_sel_hi:[1,0]
	v_pk_mul_f32 v[24:25], v[24:25], v[180:181] op_sel_hi:[1,0]
	v_pk_mul_f32 v[22:23], v[22:23], v[180:181] op_sel_hi:[1,0]
	v_pk_mul_f32 v[20:21], v[20:21], v[180:181] op_sel_hi:[1,0]
	v_pk_mul_f32 v[18:19], v[18:19], v[180:181] op_sel_hi:[1,0]
	v_pk_mul_f32 v[16:17], v[16:17], v[180:181] op_sel_hi:[1,0]
	v_mul_f32_e32 v159, v159, v180
